# cooperative grid.sync replaced by a copy of the XCD barrier; norm<true> row loads issued together
# speedup vs baseline: 1.0286x; 1.0225x over previous
.LBB0_44:
	v_lshrrev_b32_e32 v1, 20, v0
	v_lshrrev_b32_e32 v0, 10, v0
	s_waitcnt vmcnt(0) lgkmcnt(0)
	v_or_b32_e32 v0, v0, v1
	s_movk_i32 s0, 0x3ff
	v_and_or_b32 v0, v0, s0, v179
	v_cmp_eq_u32_e32 vcc, 0, v0
	s_barrier
	s_and_saveexec_b64 s[0:1], vcc
	s_cbranch_execz .LBB0_54
.LBB0_54:
	s_or_b64 exec, exec, s[0:1]
	s_add_u32 s36, s28, 0x2f00000
	s_addc_u32 s37, s29, 0
	s_add_u32 s20, s28, 0x4f00000
	s_addc_u32 s21, s29, 0
	s_add_u32 s56, s28, 0x2900000
	s_addc_u32 s57, s29, 0
	s_add_u32 s60, s28, 0x1c00000
	s_addc_u32 s61, s29, 0
	s_add_u32 s58, s28, 0x1400000
	v_readlane_b32 s12, v249, 0
	s_addc_u32 s59, s29, 0
	v_readlane_b32 s13, v249, 1
	s_add_u32 s62, s28, 0xe00000
	v_readlane_b32 s14, v249, 2
	v_readlane_b32 s15, v249, 3
	s_mov_b64 s[4:5], s[12:13]
	s_addc_u32 s63, s29, 0
	s_mov_b64 s[6:7], s[14:15]
	s_add_u32 s0, s6, 0xb00000
	s_addc_u32 s1, s7, 0
	v_readlane_b32 s16, v249, 4
	v_readlane_b32 s17, v249, 5
	v_readlane_b32 s18, v249, 6
	v_readlane_b32 s19, v249, 7
	v_writelane_b32 v249, s0, 27
	v_mov_b32_e32 v157, 0
	s_mul_i32 s31, s31, s30
	v_writelane_b32 v249, s1, 28
	s_barrier
	v_readlane_b32 s40, v249, 8
	v_readlane_b32 s52, v249, 20
	v_readlane_b32 s53, v249, 21
	s_add_u32 s0, s52, 0x400000
	s_addc_u32 s1, s53, 0
	v_readlane_b32 s41, v249, 9
	v_readlane_b32 s42, v249, 10
	v_readlane_b32 s43, v249, 11
	v_readlane_b32 s44, v249, 12
	v_readlane_b32 s45, v249, 13
	v_readlane_b32 s46, v249, 14
	v_readlane_b32 s47, v249, 15
	v_readlane_b32 s48, v249, 16
	v_readlane_b32 s49, v249, 17
	v_readlane_b32 s50, v249, 18
	v_readlane_b32 s51, v249, 19
	v_readlane_b32 s54, v249, 22
	v_readlane_b32 s55, v249, 23
	v_writelane_b32 v249, s0, 29
	s_mov_b32 s45, 0
	s_mov_b32 s65, s45
	v_writelane_b32 v249, s1, 30
	s_add_u32 s0, s84, 0xf08000
	s_addc_u32 s1, s85, 0
	v_writelane_b32 v249, s0, 31
	s_waitcnt vmcnt(0)
	buffer_inv sc1
	v_writelane_b32 v249, s1, 32
	s_add_u32 s0, s80, 0xb00000
	v_writelane_b32 v249, s72, 33
	s_addc_u32 s1, s81, 0
	s_add_u32 s88, s28, 0xc0200
	v_writelane_b32 v249, s73, 34
	v_writelane_b32 v249, s74, 35
	v_writelane_b32 v249, s75, 36
	v_writelane_b32 v249, s76, 37
	v_writelane_b32 v249, s77, 38
	v_writelane_b32 v249, s78, 39
	v_writelane_b32 v249, s79, 40
	v_writelane_b32 v249, s80, 41
	v_writelane_b32 v249, s81, 42
	v_writelane_b32 v249, s82, 43
	s_addc_u32 s89, s29, 0
	v_writelane_b32 v249, s83, 44
	s_add_u32 s50, s28, 0xc0400
	v_writelane_b32 v249, s84, 45
	s_addc_u32 s51, s29, 0
	v_writelane_b32 v249, s85, 46
	s_add_u32 s48, s28, 0xc0500
	v_writelane_b32 v249, s86, 47
	s_addc_u32 s49, s29, 0
	v_writelane_b32 v249, s87, 48
	s_add_u32 s52, s28, 0xc0600
	v_writelane_b32 v249, s0, 49
	s_addc_u32 s53, s29, 0
	s_waitcnt vmcnt(0)
	v_mov_b32_e32 v212, 0x358637bd
	v_writelane_b32 v249, s1, 50
	s_add_u32 s0, s28, 0xc0700
	s_addc_u32 s1, s29, 0
	v_writelane_b32 v249, s0, 51
	v_mov_b32_e32 v213, 1
	v_mov_b32_e32 v214, 0x100000
	v_writelane_b32 v249, s1, 52
	s_add_u32 s0, s28, 0xc0800
	s_addc_u32 s1, s29, 0
	v_writelane_b32 v249, s0, 53
	v_mov_b32_e32 v215, 0x3ecc95a3
	v_mov_b32_e32 v216, 0x9000
	v_writelane_b32 v249, s1, 54
	s_add_u32 s0, s28, 0xc0900
	s_addc_u32 s1, s29, 0
	v_writelane_b32 v249, s0, 55
	v_mov_b64_e32 v[160:161], 0x580
	v_mov_b64_e32 v[162:163], 0x57f
	v_writelane_b32 v249, s1, 56
	s_add_u32 s0, s28, 0xc0a00
	s_addc_u32 s1, s29, 0
	v_writelane_b32 v249, s0, 57
	v_mov_b64_e32 v[164:165], 0x100
	v_mov_b64_e32 v[166:167], 0xff
	v_writelane_b32 v249, s1, 58
	s_add_u32 s0, s28, 0xc0b00
	s_addc_u32 s1, s29, 0
	v_writelane_b32 v249, s0, 59
	v_mov_b64_e32 v[168:169], 0x3c0
	v_mov_b64_e32 v[170:171], 0x3bf
	v_writelane_b32 v249, s1, 60
	s_add_u32 s0, s28, 0xc0c00
	s_addc_u32 s1, s29, 0
	v_writelane_b32 v249, s0, 61
	v_mov_b32_e32 v218, 0xfffffe00
	v_mov_b32_e32 v219, 0x7f800000
	v_writelane_b32 v249, s1, 62
	s_add_u32 s0, s28, 0xc0d00
	s_addc_u32 s1, s29, 0
	v_writelane_b32 v249, s0, 63
	v_mov_b32_e32 v220, 0x1800
	v_mov_b32_e32 v221, 0x1600
	v_writelane_b32 v250, s1, 0
	s_add_u32 s0, s28, 0xc0e00
	s_addc_u32 s1, s29, 0
	v_writelane_b32 v250, s0, 1
	v_mov_b32_e32 v222, 0x1e00
	v_mov_b32_e32 v223, 0x80
	v_writelane_b32 v250, s1, 2
	s_add_u32 s0, s28, 0xc0f00
	s_addc_u32 s1, s29, 0
	v_writelane_b32 v250, s0, 3
	v_mov_b32_e32 v224, 0x41b17218
	s_mov_b32 s76, 0x1e000
	v_writelane_b32 v250, s1, 4
	s_add_u32 s0, s28, 0xc1000
	s_addc_u32 s1, s29, 0
	v_writelane_b32 v250, s0, 5
	s_mov_b32 s87, 0x9000
	s_mov_b32 s78, 0x2f00000
	v_writelane_b32 v250, s1, 6
	s_add_u32 s0, s28, 0xc1100
	s_addc_u32 s1, s29, 0
	v_writelane_b32 v250, s0, 7
	s_movk_i32 s86, 0x4000
	s_movk_i32 s72, 0x2000
	v_writelane_b32 v250, s1, 8
	s_add_u32 s0, s28, 0xc1200
	s_addc_u32 s1, s29, 0
	s_add_u32 s84, s28, 0xc1300
	s_addc_u32 s85, s29, 0
	v_writelane_b32 v250, s0, 9
	s_cmp_eq_u32 s3, 15
	s_mov_b32 s79, 0x10000
	v_writelane_b32 v250, s1, 10
	s_cselect_b64 s[0:1], -1, 0
	v_writelane_b32 v250, s0, 11
	s_cmp_eq_u32 s3, 14
	s_mov_b32 s73, 0x14000
	v_writelane_b32 v250, s1, 12
	s_cselect_b64 s[0:1], -1, 0
	v_writelane_b32 v250, s0, 13
	s_cmp_eq_u32 s3, 13
	s_movk_i32 s82, 0x1600
	v_writelane_b32 v250, s1, 14
	s_cselect_b64 s[0:1], -1, 0
	v_writelane_b32 v250, s0, 15
	s_cmp_eq_u32 s3, 12
	s_mov_b32 s83, 0xbfb8aa3b
	v_writelane_b32 v250, s1, 16
	s_cselect_b64 s[0:1], -1, 0
	v_writelane_b32 v250, s0, 17
	s_cmp_eq_u32 s3, 11
	s_movk_i32 s90, 0x1e00
	v_writelane_b32 v250, s1, 18
	s_cselect_b64 s[0:1], -1, 0
	v_writelane_b32 v250, s0, 19
	s_cmp_eq_u32 s3, 10
	s_mov_b32 s80, 0x13000
	v_writelane_b32 v250, s1, 20
	s_cselect_b64 s[0:1], -1, 0
	v_writelane_b32 v250, s0, 21
	s_cmp_eq_u32 s3, 9
	s_mov_b32 s91, 0x20000
	v_writelane_b32 v250, s1, 22
	s_cselect_b64 s[0:1], -1, 0
	v_writelane_b32 v250, s0, 23
	s_cmp_eq_u32 s3, 8
	s_mov_b32 s92, 0x30000
	v_writelane_b32 v250, s1, 24
	s_cselect_b64 s[0:1], -1, 0
	v_writelane_b32 v250, s0, 25
	s_cmp_eq_u32 s3, 7
	s_mov_b32 s77, 0x7f800000
	v_writelane_b32 v250, s1, 26
	s_cselect_b64 s[0:1], -1, 0
	v_writelane_b32 v250, s0, 27
	s_cmp_eq_u32 s3, 6
	s_mov_b32 s97, 0x3e000000
	v_writelane_b32 v250, s1, 28
	s_cselect_b64 s[0:1], -1, 0
	v_writelane_b32 v250, s0, 29
	s_cmp_eq_u32 s3, 5
	s_mov_b32 s93, 0x800000
	v_writelane_b32 v250, s1, 30
	s_cselect_b64 s[0:1], -1, 0
	v_writelane_b32 v250, s0, 31
	s_cmp_eq_u32 s3, 4
	s_mov_b32 s96, 0x3f317217
	v_writelane_b32 v250, s1, 32
	s_cselect_b64 s[0:1], -1, 0
	v_writelane_b32 v250, s0, 33
	s_cmp_eq_u32 s3, 3
	s_mov_b64 s[42:43], 0x4000
	v_writelane_b32 v250, s1, 34
	s_cselect_b64 s[0:1], -1, 0
	v_writelane_b32 v250, s0, 35
	s_cmp_eq_u32 s3, 2
	s_nop 0
	v_writelane_b32 v250, s1, 36
	s_cselect_b64 s[0:1], -1, 0
	v_writelane_b32 v250, s0, 37
	s_cmp_eq_u32 s3, 1
	s_nop 0
	v_writelane_b32 v250, s1, 38
	s_cselect_b64 s[0:1], -1, 0
	v_writelane_b32 v250, s0, 39
	s_cmp_eq_u32 s3, 0
	s_nop 0
	v_writelane_b32 v250, s1, 40
	s_cselect_b64 s[0:1], -1, 0
	v_writelane_b32 v250, s0, 41
	s_nop 1
	v_writelane_b32 v250, s1, 42
	s_lshl_b32 s0, s3, 8
	s_add_u32 s0, s10, s0
	s_addc_u32 s1, s11, 0
	s_add_u32 s4, s0, 0x1400
	s_addc_u32 s5, s1, 0
	v_writelane_b32 v250, s4, 43
	s_add_u32 s0, s0, 0x2400
	s_addc_u32 s1, s1, 0
	v_writelane_b32 v250, s5, 44
	v_writelane_b32 v250, s0, 45
	s_nop 1
	v_writelane_b32 v250, s1, 46
	s_add_u32 s0, s28, 0xc3400
	s_addc_u32 s1, s29, 0
	v_writelane_b32 v250, s0, 47
	s_nop 1
	v_writelane_b32 v250, s1, 48
	s_add_u32 s0, s28, 0xc3500
	s_addc_u32 s1, s29, 0
	s_add_u32 s17, s28, 0x300000
	s_addc_u32 s18, s29, 0
	v_writelane_b32 v250, s0, 49
	s_cmpk_lt_i32 s2, 0x580
	s_nop 0
	v_writelane_b32 v250, s1, 50
	s_cselect_b64 s[0:1], -1, 0
	v_writelane_b32 v250, s0, 51
	s_ashr_i32 s3, s2, 31
	s_ashr_i32 s33, s30, 31
	v_writelane_b32 v250, s1, 52
	s_lshr_b32 s0, s3, 29
	s_add_i32 s0, s2, s0
	s_ashr_i32 s11, s0, 3
	s_and_b32 s0, s0, -8
	s_sub_i32 s12, s2, s0
	s_cmpk_lt_i32 s2, 0x100
	s_cselect_b64 s[0:1], -1, 0
	v_writelane_b32 v250, s0, 53
	s_lshl_b32 s8, s12, 5
	s_nop 0
	v_writelane_b32 v250, s1, 54
	s_add_u32 s0, s28, 0x100000
	v_writelane_b32 v250, s0, 55
	s_addc_u32 s0, s29, 0
	s_cmpk_lt_i32 s2, 0x3c0
	v_writelane_b32 v250, s0, 56
	s_cselect_b64 s[0:1], -1, 0
	v_writelane_b32 v250, s0, 57
	s_nop 1
	v_writelane_b32 v250, s1, 58
	s_add_u32 s0, s28, 0x11f00000
	s_addc_u32 s1, s29, 0
	v_writelane_b32 v250, s0, 59
	s_nop 1
	v_writelane_b32 v250, s1, 60
	s_add_u32 s0, s28, 0xc700000
	s_addc_u32 s1, s29, 0
	s_add_u32 s14, s28, 0x11700000
	s_addc_u32 s15, s29, 0
	s_add_u32 s13, s28, 0x12700000
	s_addc_u32 s16, s29, 0
	v_writelane_b32 v250, s0, 61
	s_cmpk_lt_i32 s2, 0x400
	s_nop 0
	v_writelane_b32 v250, s1, 62
	s_cselect_b64 s[0:1], -1, 0
	v_writelane_b32 v250, s0, 63
	s_add_u32 s6, s28, 0x10700000
	s_addc_u32 s7, s29, 0
	v_writelane_b32 v251, s1, 0
	v_sub_co_u32_e64 v0, s[0:1], s2, 64
	s_xor_b64 s[0:1], s[0:1], -1
	s_nop 0
	v_writelane_b32 v251, s0, 1
	s_cmpk_lt_u32 s2, 0xc0
	v_readfirstlane_b32 s4, v0
	v_writelane_b32 v251, s1, 2
	s_cselect_b64 s[0:1], -1, 0
	v_writelane_b32 v251, s0, 3
	s_lshr_b32 s44, s4, 4
	s_and_b32 s5, s2, 3
	v_writelane_b32 v251, s1, 4
	s_lshl_b64 s[0:1], s[44:45], 11
	v_writelane_b32 v251, s0, 5
	s_nop 1
	v_writelane_b32 v251, s1, 6
	s_add_u32 s0, s28, 0x12800000
	s_addc_u32 s1, s29, 0
	v_writelane_b32 v251, s0, 7
	s_nop 1
	v_writelane_b32 v251, s1, 8
	s_lshl_b64 s[0:1], s[44:45], 22
	s_add_u32 s0, s28, s0
	s_addc_u32 s1, s29, s1
	s_add_u32 s0, s0, 0x2f00600
	s_addc_u32 s1, s1, 0
	v_writelane_b32 v251, s0, 9
	s_add_u32 s46, s28, 0xf700000
	s_addc_u32 s47, s29, 0
	v_writelane_b32 v251, s1, 10
	s_lshl_b32 s0, s4, 4
	s_and_b32 s23, s0, 0xc0
	s_lshl_b32 s10, s5, 4
	s_mul_i32 s0, s44, 0xf00000
	s_lshl_b64 s[54:55], s[44:45], 20
	s_add_u32 s0, s20, s0
	s_mul_hi_u32 s1, s44, 0xf00000
	s_addc_u32 s1, s21, s1
	s_lshl_b32 s4, s23, 1
	s_add_u32 s0, s0, s4
	s_addc_u32 s1, s1, 0
	s_lshl_b32 s4, s5, 5
	v_writelane_b32 v251, s54, 11
	s_add_u32 s0, s0, s4
	s_addc_u32 s1, s1, 0
	v_writelane_b32 v251, s55, 12
	v_writelane_b32 v251, s0, 13
	s_nop 1
	v_writelane_b32 v251, s1, 14
	v_sub_co_u32_e64 v156, s[0:1], s5, 1
	s_and_b64 s[0:1], s[0:1], exec
	s_cselect_b32 s39, 10, 8
	s_lshr_b32 s44, s2, 1
	s_add_u32 s0, s28, 0xd700000
	v_writelane_b32 v251, s5, 15
	s_addc_u32 s1, s29, 0
	v_writelane_b32 v251, s0, 16
	s_add_u32 s54, s28, 0xe700000
	s_addc_u32 s55, s29, 0
	v_writelane_b32 v251, s1, 17
	s_lshl_b32 s0, s2, 8
	s_lshl_b32 s9, s2, 6
	s_and_b32 s19, s9, 0x180
	v_writelane_b32 v251, s0, 18
	s_and_b32 s64, s0, 0x3800
	s_lshl_b64 s[0:1], s[44:45], 19
	s_add_u32 s4, s6, s0
	v_writelane_b32 v251, s6, 19
	s_addc_u32 s5, s7, s1
	v_lshlrev_b64 v[0:1], 23, v[156:157]
	v_writelane_b32 v251, s7, 20
	v_writelane_b32 v251, s4, 21
	s_nop 1
	v_writelane_b32 v251, s5, 22
	s_lshl_b32 s4, s19, 1
	s_add_u32 s4, s54, s4
	v_writelane_b32 v251, s54, 23
	s_addc_u32 s5, s55, 0
	s_nop 0
	v_writelane_b32 v251, s55, 24
	v_writelane_b32 v251, s9, 25
	s_and_b32 s9, s9, 64
	s_lshl_b32 s6, s9, 1
	s_add_u32 s4, s4, s6
	s_addc_u32 s5, s5, 0
	v_writelane_b32 v251, s4, 26
	s_nop 1
	v_writelane_b32 v251, s5, 27
	s_lshl_b64 s[4:5], s[44:45], 18
	s_add_u32 s6, s14, s4
	v_writelane_b32 v251, s14, 28
	s_addc_u32 s7, s15, s5
	s_nop 0
	v_writelane_b32 v251, s15, 29
	v_writelane_b32 v251, s6, 30
	s_nop 1
	v_writelane_b32 v251, s7, 31
	s_lshl_b64 s[6:7], s[44:45], 7
	v_writelane_b32 v251, s13, 32
	s_add_u32 s14, s13, s6
	v_writelane_b32 v251, s16, 33
	s_addc_u32 s15, s16, s7
	v_writelane_b32 v251, s14, 34
	s_or_b32 s9, s19, s9
	s_nop 0
	v_writelane_b32 v251, s15, 35
	v_writelane_b32 v251, s19, 36
	v_writelane_b32 v251, s9, 37
	s_add_u32 s9, s28, 0xc8000
	v_writelane_b32 v251, s9, 38
	s_addc_u32 s9, s29, 0
	s_add_u32 s44, s28, 0x1e00000
	s_addc_u32 s54, s29, 0
	v_writelane_b32 v251, s9, 39
	s_cmp_lt_i32 s12, 0
	s_mul_i32 s9, s12, 33
	s_cselect_b32 s13, s9, s8
	s_movk_i32 s8, 0xb1
	s_cselect_b32 s8, s8, 0xb0
	s_mul_i32 s8, s12, s8
	s_movk_i32 s9, 0x79
	s_cselect_b32 s16, s9, 0x78
	s_add_i32 s8, s8, s11
	s_mul_hi_i32 s9, s8, 0x2e8ba2e9
	s_lshr_b32 s14, s9, 31
	s_ashr_i32 s9, s9, 5
	s_add_i32 s9, s9, s14
	s_mul_i32 s14, s9, 0xb0
	s_sub_i32 s8, s8, s14
	s_bfe_u32 s14, s8, 0x3001c
	s_add_i32 s14, s8, s14
	s_and_b32 s15, s14, 0xfff8
	s_sub_i32 s8, s8, s15
	s_lshl_b32 s9, s9, 3
	s_sext_i32_i16 s14, s14
	s_sext_i32_i16 s8, s8
	s_add_i32 s66, s9, s8
	s_ashr_i32 s8, s14, 3
	v_writelane_b32 v251, s8, 40
	s_lshr_b32 s8, s14, 3
	s_mov_b32 s14, s66
	s_ashr_i32 s67, s66, 31
	s_bfe_i64 s[8:9], s[8:9], 0x100000
	v_writelane_b32 v251, s14, 41
	s_lshl_b64 s[8:9], s[8:9], 19
	s_mul_i32 s12, s12, s16
	v_writelane_b32 v251, s15, 42
	s_lshl_b64 s[14:15], s[66:67], 19
	s_add_u32 s66, s17, s8
	v_writelane_b32 v251, s17, 43
	s_addc_u32 s67, s18, s9
	v_writelane_b32 v251, s18, 44
	s_add_u32 s18, s66, 0x40000
	s_addc_u32 s19, s67, 0
	v_writelane_b32 v251, s18, 45
	s_add_u32 s14, s36, s14
	s_addc_u32 s15, s37, s15
	v_writelane_b32 v251, s19, 46
	s_add_u32 s18, s14, 0x40000
	v_writelane_b32 v251, s14, 47
	s_addc_u32 s19, s15, 0
	s_nop 0
	v_writelane_b32 v251, s15, 48
	v_writelane_b32 v251, s18, 49
	s_add_u32 s14, s66, 0x40080
	s_nop 0
	v_writelane_b32 v251, s19, 50
	v_writelane_b32 v251, s66, 51
	s_addc_u32 s15, s67, 0
	s_add_i32 s13, s13, s11
	v_writelane_b32 v251, s67, 52
	v_writelane_b32 v251, s14, 53
	s_nop 1
	v_writelane_b32 v251, s15, 54
	s_ashr_i32 s14, s13, 31
	s_lshr_b32 s14, s14, 27
	s_add_i32 s14, s13, s14
	s_and_b32 s15, s14, 0xffe0
	s_sub_i32 s13, s13, s15
	s_bfe_i32 s15, s13, 0x80000
	s_bfe_u32 s15, s15, 0x3000c
	s_add_i32 s15, s13, s15
	s_and_b32 s17, s15, 0xf8
	s_sub_i32 s13, s13, s17
	s_ashr_i32 s14, s14, 5
	s_bfe_i32 s15, s15, 0x80000
	s_lshl_b32 s14, s14, 3
	s_sext_i32_i16 s15, s15
	s_sext_i32_i8 s13, s13
	s_add_i32 s66, s14, s13
	s_ashr_i32 s13, s15, 3
	s_lshr_b32 s14, s15, 3
	s_ashr_i32 s67, s66, 31
	s_bfe_i64 s[14:15], s[14:15], 0x100000
	s_mul_i32 s19, s13, 0x160000
	s_mul_hi_i32 s18, s13, 0x160000
	v_writelane_b32 v251, s13, 55
	s_add_u32 s68, s62, s19
	v_writelane_b32 v251, s62, 56
	s_addc_u32 s69, s63, s18
	s_add_u32 s40, s68, 0xb0000
	v_writelane_b32 v251, s63, 57
	s_addc_u32 s41, s69, 0
	v_writelane_b32 v251, s40, 58
	s_mul_i32 s17, s66, 0x160000
	s_mul_hi_i32 s13, s66, 0x160000
	v_writelane_b32 v251, s41, 59
	s_add_u32 s40, s20, s17
	s_addc_u32 s41, s21, s13
	s_add_u32 s16, s40, 0xb0000
	v_writelane_b32 v251, s40, 60
	s_addc_u32 s17, s41, 0
	s_mul_i32 s62, s31, s22
	v_writelane_b32 v251, s41, 61
	v_writelane_b32 v251, s16, 62
	s_mov_b32 s31, 0
	s_nop 0
	v_writelane_b32 v251, s17, 63
	s_add_u32 s16, s68, 0xb0080
	v_writelane_b32 v252, s68, 0
	s_addc_u32 s17, s69, 0
	s_add_i32 s12, s12, s11
	s_mul_hi_i32 s11, s12, 0x88888889
	s_add_i32 s11, s11, s12
	s_lshr_b32 s13, s11, 31
	s_ashr_i32 s11, s11, 6
	s_add_i32 s11, s11, s13
	s_mul_i32 s13, s11, 0x78
	s_sub_i32 s12, s12, s13
	s_bfe_i32 s13, s12, 0x80000
	v_writelane_b32 v252, s69, 1
	s_bfe_u32 s13, s13, 0x3000c
	v_writelane_b32 v252, s16, 2
	s_add_i32 s13, s12, s13
	s_lshl_b32 s11, s11, 3
	v_writelane_b32 v252, s17, 3
	s_and_b32 s16, s13, 0xf8
	s_sub_i32 s12, s12, s16
	s_bfe_i32 s13, s13, 0x80000
	s_sext_i32_i16 s13, s13
	s_sext_i32_i8 s12, s12
	s_add_i32 s40, s11, s12
	s_ashr_i32 s11, s13, 3
	v_writelane_b32 v252, s11, 4
	s_lshr_b32 s12, s13, 3
	s_mov_b32 s16, s40
	s_ashr_i32 s41, s40, 31
	s_bfe_i64 s[12:13], s[12:13], 0x100000
	v_writelane_b32 v252, s16, 5
	s_lshl_b64 s[12:13], s[12:13], 19
	s_mov_b64 s[68:69], 0x400
	v_writelane_b32 v252, s17, 6
	s_lshl_b64 s[16:17], s[40:41], 19
	s_add_u32 s12, s58, s12
	v_writelane_b32 v252, s58, 7
	s_addc_u32 s13, s59, s13
	s_add_u32 s40, s12, 0x40000
	v_writelane_b32 v252, s59, 8
	s_addc_u32 s41, s13, 0
	v_writelane_b32 v252, s40, 9
	s_add_u32 s16, s36, s16
	s_addc_u32 s17, s37, s17
	v_writelane_b32 v252, s41, 10
	s_add_u32 s40, s16, 0x40000
	v_writelane_b32 v252, s16, 11
	s_addc_u32 s41, s17, 0
	s_nop 0
	v_writelane_b32 v252, s17, 12
	v_writelane_b32 v252, s40, 13
	s_add_u32 s16, s12, 0x40080
	s_nop 0
	v_writelane_b32 v252, s41, 14
	v_writelane_b32 v252, s12, 15
	s_addc_u32 s17, s13, 0
	s_nop 0
	v_writelane_b32 v252, s13, 16
	v_writelane_b32 v252, s16, 17
	s_lshl_b64 s[12:13], s[14:15], 19
	s_mov_b32 s14, s66
	v_writelane_b32 v252, s17, 18
	v_writelane_b32 v252, s14, 19
	s_nop 1
	v_writelane_b32 v252, s15, 20
	s_lshl_b64 s[14:15], s[66:67], 19
	s_add_u32 s12, s60, s12
	s_addc_u32 s13, s61, s13
	s_add_u32 s16, s12, 0x40000
	s_addc_u32 s17, s13, 0
	v_writelane_b32 v252, s16, 21
	s_add_u32 s14, s36, s14
	s_addc_u32 s15, s37, s15
	v_writelane_b32 v252, s17, 22
	s_add_u32 s16, s14, 0x40000
	v_writelane_b32 v252, s14, 23
	s_addc_u32 s17, s15, 0
	s_mov_b64 s[66:67], 0x1000
	v_writelane_b32 v252, s15, 24
	v_writelane_b32 v252, s16, 25
	s_add_u32 s14, s12, 0x40080
	s_nop 0
	v_writelane_b32 v252, s17, 26
	v_writelane_b32 v252, s12, 27
	s_addc_u32 s15, s13, 0
	s_add_u32 s8, s44, s8
	v_writelane_b32 v252, s13, 28
	v_writelane_b32 v252, s14, 29
	s_addc_u32 s9, s54, s9
	s_add_u32 s12, s8, 0x40000
	v_writelane_b32 v252, s15, 30
	v_writelane_b32 v252, s44, 31
	v_writelane_b32 v252, s54, 32
	s_addc_u32 s13, s9, 0
	v_writelane_b32 v252, s12, 33
	s_nop 1
	v_writelane_b32 v252, s13, 34
	s_add_u32 s12, s8, 0x40080
	v_writelane_b32 v252, s8, 35
	s_addc_u32 s13, s9, 0
	s_nop 0
	v_writelane_b32 v252, s9, 36
	v_writelane_b32 v252, s12, 37
	s_add_u32 s8, s56, s19
	s_nop 0
	v_writelane_b32 v252, s13, 38
	v_writelane_b32 v252, s56, 39
	s_addc_u32 s9, s57, s18
	s_add_u32 s12, s8, 0xb0000
	v_writelane_b32 v252, s57, 40
	s_addc_u32 s13, s9, 0
	v_writelane_b32 v252, s12, 41
	s_nop 1
	v_writelane_b32 v252, s13, 42
	s_add_u32 s12, s8, 0xb0080
	v_writelane_b32 v252, s8, 43
	s_addc_u32 s13, s9, 0
	s_nop 0
	v_writelane_b32 v252, s9, 44
	v_writelane_b32 v252, s12, 45
	s_lshl_b32 s8, s2, 7
	s_lshl_b32 s9, s2, 18
	v_writelane_b32 v252, s13, 46
	s_and_b32 s8, s8, 0x300
	s_and_b32 s12, s9, 0xe00000
	s_and_b32 s9, s2, 1
	s_or_b32 s8, s12, s8
	s_lshl_b32 s9, s9, 7
	s_or_b32 s8, s8, s9
	v_writelane_b32 v252, s23, 47
	s_or_b32 s9, s10, s23
	v_writelane_b32 v252, s9, 48
	s_lshl_b32 s9, s2, 4
	s_add_i32 s9, s9, 0x7fffd000
	v_writelane_b32 v252, s9, 49
	s_lshl_b32 s9, s30, 4
	v_writelane_b32 v252, s9, 50
	s_lshl_b32 s9, s30, 8
	v_writelane_b32 v252, s9, 51
	s_lshl_b32 s9, s30, 6
	v_writelane_b32 v252, s9, 52
	s_lshl_b32 s9, s2, 9
	v_writelane_b32 v252, s9, 53
	s_lshl_b32 s9, s30, 9
	s_add_u32 s8, s8, 0xe710000
	v_writelane_b32 v252, s9, 54
	s_addc_u32 s9, 0, 0
	v_writelane_b32 v252, s8, 55
	s_add_u32 s6, s6, 0x12700004
	s_addc_u32 s7, s7, 0
	v_writelane_b32 v252, s9, 56
	v_writelane_b32 v252, s6, 57
	s_add_u32 s4, s4, 0x11702000
	s_addc_u32 s5, s5, 0
	v_writelane_b32 v252, s7, 58
	v_writelane_b32 v252, s4, 59
	s_add_u32 s0, s0, 0x10704000
	s_addc_u32 s1, s1, 0
	v_writelane_b32 v252, s5, 60
	v_writelane_b32 v252, s0, 61
	s_mov_b32 s13, s45
	s_mov_b64 s[4:5], 0
	v_writelane_b32 v252, s1, 62
	v_writelane_b32 v252, s46, 63
	s_add_u32 s0, s26, 0xc00
	s_addc_u32 s1, s27, 0
	v_writelane_b32 v253, s47, 0
	v_writelane_b32 v253, s64, 1
	v_lshl_add_u64 v[158:159], s[46:47], 0, v[0:1]
	s_mov_b64 s[22:23], s[70:71]
	v_writelane_b32 v253, s65, 2
	v_writelane_b32 v253, s12, 3
	v_mbcnt_lo_u32_b32 v0, -1, 0
	v_mbcnt_hi_u32_b32 v217, -1, v0
	v_writelane_b32 v253, s13, 4
	v_writelane_b32 v253, s0, 5
	s_mov_b64 s[64:65], 0x80
	s_nop 0
	v_writelane_b32 v253, s1, 6
	s_add_i32 s0, 0, 0x23ff0
	v_writelane_b32 v253, s0, 7
	s_add_i32 s0, 0, 0x23ff4
	v_writelane_b32 v253, s0, 8
	s_add_i32 s0, 0, 0x11200
	v_writelane_b32 v253, s0, 9
	s_add_i32 s0, 0, 0x11300
	v_writelane_b32 v253, s0, 10
	s_add_i32 s0, 0, 0x8800
	v_writelane_b32 v253, s0, 11
	s_add_i32 s0, 0, 0x11100
	v_writelane_b32 v253, s0, 12
	s_add_i32 s0, 0, 0x4400
	v_writelane_b32 v253, s0, 13
	s_add_i32 s0, 0, 0x112fc
	v_writelane_b32 v253, s0, 14
	s_add_i32 s0, 0, 0x113fc
	v_writelane_b32 v253, s0, 15
	s_add_i32 s0, 0, 0x11400
	v_writelane_b32 v253, s0, 16
	v_writelane_b32 v253, s60, 17
	s_mov_b64 s[0:1], -1
	s_nop 0
	v_writelane_b32 v253, s61, 18
	v_writelane_b32 v253, s88, 19
	s_nop 1
	v_writelane_b32 v253, s89, 20
	v_writelane_b32 v253, s50, 21
	s_nop 1
	v_writelane_b32 v253, s51, 22
	v_writelane_b32 v253, s48, 23
	s_nop 1
	v_writelane_b32 v253, s49, 24
	v_writelane_b32 v253, s52, 25
	s_nop 1
	v_writelane_b32 v253, s53, 26
	v_writelane_b32 v253, s62, 27
.Lgs_84:
	s_waitcnt vmcnt(0)
	s_barrier
	s_and_saveexec_b64 s[4:5], s[22:23]
	s_cbranch_execz .Lgs_136
	v_readlane_b32 s8, v253, 7
	s_waitcnt vmcnt(0) expcnt(0) lgkmcnt(0)
	s_nop 0
	v_mov_b32_e32 v0, s8
	ds_read_b32 v2, v0
	v_readlane_b32 s8, v253, 8
	s_waitcnt lgkmcnt(0)
	v_cmp_ne_u32_e32 vcc, 0, v2
	v_mov_b32_e32 v0, s8
	ds_read_b32 v0, v0
	s_cbranch_vccnz .Lgs_100
	s_mov_b32 s14, 1
	s_branch .Lgs_88

.Lgs_136:
	s_or_b64 exec, exec, s[4:5]
	s_waitcnt lgkmcnt(0)
	s_barrier
	s_mov_b64 s[4:5], 0
	s_branch .LBB0_57

.LBB0_297:
	v_lshl_add_u64 v[144:145], v[184:185], 0, s[8:9]
	global_load_dwordx4 v[202:205], v[144:145], off
	s_waitcnt lgkmcnt(6)
	global_load_dwordx4 v[152:155], v[144:145], off offset:1024
	global_load_dwordx4 v[148:151], v[144:145], off offset:2048
	s_nop 0
	global_load_dwordx4 v[144:147], v[144:145], off offset:3072
	s_waitcnt vmcnt(3) lgkmcnt(0)
	v_pk_mul_f32 v[242:243], v[204:205], v[204:205]
	v_pk_mul_f32 v[244:245], v[202:203], v[202:203]
	s_nop 0
	v_pk_mov_b32 v[246:247], v[244:245], v[242:243] op_sel:[1,0]
	v_mov_b32_e32 v245, v243
	v_pk_add_f32 v[206:207], v[246:247], v[244:245]
	s_waitcnt vmcnt(2)
	v_pk_mul_f32 v[242:243], v[154:155], v[154:155]
	v_pk_mul_f32 v[244:245], v[152:153], v[152:153]
	v_pk_add_f32 v[206:207], v[206:207], v[206:207] op_sel:[0,1] op_sel_hi:[1,0]
	v_pk_mov_b32 v[246:247], v[244:245], v[242:243] op_sel:[1,0]
	v_mov_b32_e32 v245, v243
	v_pk_add_f32 v[208:209], v[246:247], v[244:245]
	v_pk_add_f32 v[208:209], v[208:209], v[208:209] op_sel:[0,1] op_sel_hi:[1,0]
	s_waitcnt vmcnt(0)
	v_mul_f32_e32 v156, v144, v144
	v_mul_f32_e32 v210, v145, v145
	v_mov_b32_e32 v207, v156
	v_mov_b32_e32 v209, v210
	v_mul_f32_e32 v156, v149, v149
	v_mul_f32_e32 v211, v146, v146
	v_pk_add_f32 v[206:207], v[206:207], v[208:209]
	v_pk_fma_f32 v[208:209], v[148:149], v[148:149], v[156:157] op_sel_hi:[1,1,0]
	v_mul_f32_e32 v156, v151, v151
	v_mul_f32_e32 v231, v147, v147
	v_mov_b32_e32 v209, v211
	v_pk_fma_f32 v[210:211], v[150:151], v[150:151], v[156:157] op_sel_hi:[1,1,0]
	s_nop 0
	v_mov_b32_e32 v211, v231
	v_pk_add_f32 v[208:209], v[208:209], v[210:211]
	s_nop 0
	v_pk_add_f32 v[206:207], v[206:207], v[208:209]
	s_nop 0
	v_add_f32_e32 v156, v206, v207
	s_nop 1
	v_add_f32_dpp v156, v156, v156 quad_perm:[1,0,3,2] row_mask:0xf bank_mask:0xf bound_ctrl:1
	s_nop 1
	v_add_f32_dpp v156, v156, v156 quad_perm:[2,3,0,1] row_mask:0xf bank_mask:0xf bound_ctrl:1
	s_nop 1
	v_add_f32_dpp v156, v156, v156 row_half_mirror row_mask:0xf bank_mask:0xf bound_ctrl:1
	s_nop 1
	v_add_f32_dpp v156, v156, v156 row_mirror row_mask:0xf bank_mask:0xf bound_ctrl:1
	s_nop 0
	v_readlane_b32 s5, v156, 16
	v_readlane_b32 s11, v156, 48
	v_readlane_b32 s0, v156, 0
	v_readlane_b32 s1, v156, 32
	v_mov_b32_e32 v206, s5
	v_mov_b32_e32 v207, s11
	v_pk_add_f32 v[206:207], s[0:1], v[206:207]
	s_nop 0
	v_add_f32_e32 v156, v206, v207
	v_fmamk_f32 v156, v156, 0x3a800000, v212
	v_rsq_f32_e32 v156, v156
	v_lshl_add_u64 v[206:207], s[28:29], 0, v[182:183]
	v_add_co_u32_e64 v210, s[0:1], s78, v206
	v_pk_mul_f32 v[208:209], v[202:203], v[156:157] op_sel_hi:[1,0]
	s_nop 0
	v_addc_co_u32_e64 v211, s[0:1], 0, v207, s[0:1]
	v_pk_mul_f32 v[206:207], v[152:153], v[156:157] op_sel_hi:[1,0]
	v_pk_mul_f32 v[152:153], v[154:155], v[156:157] op_sel_hi:[1,0]
	v_pk_fma_f32 v[206:207], v[192:193], v[206:207], v[132:133]
	v_pk_fma_f32 v[152:153], v[190:191], v[152:153], v[134:135]
	v_cvt_pk_bf16_f32 v154, v206, v207
	v_cvt_pk_bf16_f32 v155, v152, v153
	global_store_dwordx2 v[210:211], v[154:155], off offset:512
	v_pk_mul_f32 v[154:155], v[148:149], v[156:157] op_sel_hi:[1,0]
	v_pk_mul_f32 v[148:149], v[150:151], v[156:157] op_sel_hi:[1,0]
	v_pk_fma_f32 v[150:151], v[196:197], v[154:155], v[136:137]
	v_pk_fma_f32 v[148:149], v[194:195], v[148:149], v[138:139]
	v_cvt_pk_bf16_f32 v154, v150, v151
	v_cvt_pk_bf16_f32 v155, v148, v149
	global_store_dwordx2 v[210:211], v[154:155], off offset:1024
	v_pk_mul_f32 v[154:155], v[144:145], v[156:157] op_sel_hi:[1,0]
	v_pk_mul_f32 v[144:145], v[146:147], v[156:157] op_sel_hi:[1,0]
	v_pk_fma_f32 v[146:147], v[200:201], v[154:155], v[140:141]
	v_pk_fma_f32 v[144:145], v[198:199], v[144:145], v[142:143]
	v_pk_mul_f32 v[202:203], v[204:205], v[156:157] op_sel_hi:[1,0]
	v_pk_fma_f32 v[204:205], v[188:189], v[208:209], v[128:129]
	v_cvt_pk_bf16_f32 v154, v146, v147
	v_cvt_pk_bf16_f32 v155, v144, v145
	global_store_dwordx2 v[210:211], v[154:155], off offset:1536
	s_waitcnt lgkmcnt(14)
	v_pk_fma_f32 v[154:155], v[0:1], v[204:205], 0 op_sel_hi:[1,0,0]
	v_pk_fma_f32 v[202:203], v[186:187], v[202:203], v[130:131]
	v_pk_fma_f32 v[154:155], v[8:9], v[204:205], v[154:155] op_sel:[0,1,0]
	v_cvt_pk_bf16_f32 v208, v204, v205
	v_pk_fma_f32 v[154:155], v[16:17], v[202:203], v[154:155] op_sel_hi:[1,0,1]
	v_cvt_pk_bf16_f32 v209, v202, v203
	v_pk_fma_f32 v[154:155], v[202:203], v[24:25], v[154:155] op_sel:[1,0,0]
	global_store_dwordx2 v[210:211], v[208:209], off
	v_pk_fma_f32 v[154:155], v[206:207], v[32:33], v[154:155] op_sel_hi:[0,1,1]
	v_pk_fma_f32 v[154:155], v[206:207], v[40:41], v[154:155] op_sel:[1,0,0]
	v_pk_fma_f32 v[232:233], v[6:7], v[204:205], 0 op_sel_hi:[1,0,0]
	v_pk_fma_f32 v[154:155], v[152:153], v[48:49], v[154:155] op_sel_hi:[0,1,1]
	v_pk_fma_f32 v[154:155], v[152:153], v[56:57], v[154:155] op_sel:[1,0,0]
	s_nop 0
	v_pk_fma_f32 v[154:155], v[150:151], v[64:65], v[154:155] op_sel_hi:[0,1,1]
	s_waitcnt lgkmcnt(13)
	v_pk_fma_f32 v[154:155], v[150:151], v[72:73], v[154:155] op_sel:[1,0,0]
	s_waitcnt lgkmcnt(11)
	v_pk_fma_f32 v[210:211], v[148:149], v[80:81], v[154:155] op_sel_hi:[0,1,1]
	v_pk_fma_f32 v[154:155], v[2:3], v[204:205], 0 op_sel_hi:[1,0,0]
	s_nop 0
	v_pk_fma_f32 v[154:155], v[10:11], v[204:205], v[154:155] op_sel:[0,1,0]
	s_nop 0
	v_pk_fma_f32 v[154:155], v[18:19], v[202:203], v[154:155] op_sel_hi:[1,0,1]
	s_nop 0
	v_pk_fma_f32 v[154:155], v[202:203], v[26:27], v[154:155] op_sel:[1,0,0]
	s_nop 0
	v_pk_fma_f32 v[154:155], v[206:207], v[34:35], v[154:155] op_sel_hi:[0,1,1]
	v_pk_fma_f32 v[154:155], v[206:207], v[42:43], v[154:155] op_sel:[1,0,0]
	s_nop 0
	v_pk_fma_f32 v[154:155], v[152:153], v[50:51], v[154:155] op_sel_hi:[0,1,1]
	v_pk_fma_f32 v[154:155], v[152:153], v[58:59], v[154:155] op_sel:[1,0,0]
	s_nop 0
	v_pk_fma_f32 v[154:155], v[150:151], v[66:67], v[154:155] op_sel_hi:[0,1,1]
	v_pk_fma_f32 v[154:155], v[150:151], v[74:75], v[154:155] op_sel:[1,0,0]
	s_nop 0
	v_pk_fma_f32 v[208:209], v[148:149], v[82:83], v[154:155] op_sel_hi:[0,1,1]
	v_pk_fma_f32 v[154:155], v[4:5], v[204:205], 0 op_sel_hi:[1,0,0]
	s_nop 0
	v_pk_fma_f32 v[154:155], v[12:13], v[204:205], v[154:155] op_sel:[0,1,0]
	v_pk_fma_f32 v[204:205], v[14:15], v[204:205], v[232:233] op_sel:[0,1,0]
	v_pk_fma_f32 v[154:155], v[202:203], v[20:21], v[154:155] op_sel_hi:[0,1,1]
	v_pk_fma_f32 v[204:205], v[202:203], v[22:23], v[204:205] op_sel_hi:[0,1,1]
	v_pk_fma_f32 v[154:155], v[202:203], v[28:29], v[154:155] op_sel:[1,0,0]
	v_pk_fma_f32 v[202:203], v[202:203], v[30:31], v[204:205] op_sel:[1,0,0]
	v_pk_fma_f32 v[154:155], v[206:207], v[36:37], v[154:155] op_sel_hi:[0,1,1]
	v_pk_fma_f32 v[202:203], v[206:207], v[38:39], v[202:203] op_sel_hi:[0,1,1]
	v_pk_fma_f32 v[154:155], v[206:207], v[44:45], v[154:155] op_sel:[1,0,0]
	v_pk_fma_f32 v[202:203], v[206:207], v[46:47], v[202:203] op_sel:[1,0,0]
	v_pk_fma_f32 v[154:155], v[152:153], v[52:53], v[154:155] op_sel_hi:[0,1,1]
	v_pk_fma_f32 v[202:203], v[152:153], v[54:55], v[202:203] op_sel_hi:[0,1,1]
	v_pk_fma_f32 v[154:155], v[152:153], v[60:61], v[154:155] op_sel:[1,0,0]
	v_pk_fma_f32 v[152:153], v[152:153], v[62:63], v[202:203] op_sel:[1,0,0]
	v_pk_fma_f32 v[154:155], v[150:151], v[68:69], v[154:155] op_sel_hi:[0,1,1]
	v_pk_fma_f32 v[152:153], v[150:151], v[70:71], v[152:153] op_sel_hi:[0,1,1]
	v_pk_fma_f32 v[154:155], v[150:151], v[76:77], v[154:155] op_sel:[1,0,0]
	v_pk_fma_f32 v[150:151], v[150:151], v[78:79], v[152:153] op_sel:[1,0,0]
	s_waitcnt lgkmcnt(10)
	v_pk_fma_f32 v[154:155], v[148:149], v[84:85], v[154:155] op_sel_hi:[0,1,1]
	v_pk_fma_f32 v[202:203], v[148:149], v[86:87], v[150:151] op_sel_hi:[0,1,1]
	s_waitcnt lgkmcnt(9)
	v_pk_fma_f32 v[150:151], v[148:149], v[88:89], v[210:211] op_sel:[1,0,0]
	v_pk_fma_f32 v[204:205], v[148:149], v[90:91], v[208:209] op_sel:[1,0,0]
	s_waitcnt lgkmcnt(8)
	v_pk_fma_f32 v[154:155], v[148:149], v[92:93], v[154:155] op_sel:[1,0,0]
	v_pk_fma_f32 v[148:149], v[148:149], v[94:95], v[202:203] op_sel:[1,0,0]
	s_waitcnt lgkmcnt(7)
	v_pk_fma_f32 v[150:151], v[146:147], v[96:97], v[150:151] op_sel_hi:[0,1,1]
	v_pk_fma_f32 v[204:205], v[146:147], v[98:99], v[204:205] op_sel_hi:[0,1,1]
	s_waitcnt lgkmcnt(6)
	v_pk_fma_f32 v[154:155], v[146:147], v[100:101], v[154:155] op_sel_hi:[0,1,1]
	v_pk_fma_f32 v[148:149], v[146:147], v[102:103], v[148:149] op_sel_hi:[0,1,1]
	s_waitcnt lgkmcnt(5)
	v_pk_fma_f32 v[150:151], v[146:147], v[104:105], v[150:151] op_sel:[1,0,0]
	v_pk_fma_f32 v[204:205], v[146:147], v[106:107], v[204:205] op_sel:[1,0,0]
	s_waitcnt lgkmcnt(4)
	v_pk_fma_f32 v[154:155], v[146:147], v[108:109], v[154:155] op_sel:[1,0,0]
	v_pk_fma_f32 v[146:147], v[146:147], v[110:111], v[148:149] op_sel:[1,0,0]
	s_waitcnt lgkmcnt(3)
	v_pk_fma_f32 v[150:151], v[144:145], v[112:113], v[150:151] op_sel_hi:[0,1,1]
	v_pk_fma_f32 v[204:205], v[144:145], v[114:115], v[204:205] op_sel_hi:[0,1,1]
	s_waitcnt lgkmcnt(2)
	v_pk_fma_f32 v[154:155], v[144:145], v[116:117], v[154:155] op_sel_hi:[0,1,1]
	v_pk_fma_f32 v[146:147], v[144:145], v[118:119], v[146:147] op_sel_hi:[0,1,1]
	s_waitcnt lgkmcnt(1)
	v_pk_fma_f32 v[150:151], v[144:145], v[120:121], v[150:151] op_sel:[1,0,0]
	v_pk_fma_f32 v[204:205], v[144:145], v[122:123], v[204:205] op_sel:[1,0,0]
	s_waitcnt lgkmcnt(0)
	v_pk_fma_f32 v[154:155], v[144:145], v[124:125], v[154:155] op_sel:[1,0,0]
	v_pk_fma_f32 v[144:145], v[144:145], v[126:127], v[146:147] op_sel:[1,0,0]
	ds_bpermute_b32 v152, v225, v150
	ds_bpermute_b32 v153, v225, v151
	ds_bpermute_b32 v206, v225, v204
	ds_bpermute_b32 v207, v225, v205
	ds_bpermute_b32 v208, v225, v154
	ds_bpermute_b32 v209, v225, v155
	ds_bpermute_b32 v146, v225, v144
	ds_bpermute_b32 v147, v225, v145
	s_waitcnt lgkmcnt(6)
	v_pk_add_f32 v[150:151], v[150:151], v[152:153]
	s_waitcnt lgkmcnt(4)
	v_pk_add_f32 v[204:205], v[204:205], v[206:207]
	s_waitcnt lgkmcnt(2)
	v_pk_add_f32 v[154:155], v[154:155], v[208:209]
	ds_bpermute_b32 v152, v226, v150
	s_waitcnt lgkmcnt(1)
	v_pk_add_f32 v[144:145], v[144:145], v[146:147]
	ds_bpermute_b32 v153, v226, v151
	ds_bpermute_b32 v206, v226, v204
	ds_bpermute_b32 v207, v226, v205
	ds_bpermute_b32 v208, v226, v154
	ds_bpermute_b32 v209, v226, v155
	ds_bpermute_b32 v146, v226, v144
	ds_bpermute_b32 v147, v226, v145
	s_waitcnt lgkmcnt(6)
	v_pk_add_f32 v[150:151], v[150:151], v[152:153]
	s_waitcnt lgkmcnt(4)
	v_pk_add_f32 v[204:205], v[204:205], v[206:207]
	s_waitcnt lgkmcnt(2)
	v_pk_add_f32 v[154:155], v[154:155], v[208:209]
	ds_bpermute_b32 v152, v227, v150
	s_waitcnt lgkmcnt(1)
	v_pk_add_f32 v[144:145], v[144:145], v[146:147]
	ds_bpermute_b32 v153, v227, v151
	ds_bpermute_b32 v206, v227, v204
	ds_bpermute_b32 v207, v227, v205
	ds_bpermute_b32 v208, v227, v154
	ds_bpermute_b32 v209, v227, v155
	ds_bpermute_b32 v146, v227, v144
	ds_bpermute_b32 v147, v227, v145
	s_waitcnt lgkmcnt(6)
	v_pk_add_f32 v[150:151], v[150:151], v[152:153]
	s_waitcnt lgkmcnt(4)
	v_pk_add_f32 v[204:205], v[204:205], v[206:207]
	s_waitcnt lgkmcnt(2)
	v_pk_add_f32 v[154:155], v[154:155], v[208:209]
	ds_bpermute_b32 v152, v228, v150
	s_waitcnt lgkmcnt(1)
	v_pk_add_f32 v[144:145], v[144:145], v[146:147]
	ds_bpermute_b32 v153, v228, v151
	ds_bpermute_b32 v206, v228, v204
	ds_bpermute_b32 v207, v228, v205
	ds_bpermute_b32 v208, v228, v154
	ds_bpermute_b32 v209, v228, v155
	ds_bpermute_b32 v146, v228, v144
	ds_bpermute_b32 v147, v228, v145
	s_waitcnt lgkmcnt(6)
	v_pk_add_f32 v[150:151], v[150:151], v[152:153]
	s_waitcnt lgkmcnt(4)
	v_pk_add_f32 v[204:205], v[204:205], v[206:207]
	s_waitcnt lgkmcnt(2)
	v_pk_add_f32 v[154:155], v[154:155], v[208:209]
	ds_bpermute_b32 v152, v229, v150
	s_waitcnt lgkmcnt(1)
	v_pk_add_f32 v[144:145], v[144:145], v[146:147]
	ds_bpermute_b32 v153, v229, v151
	ds_bpermute_b32 v206, v229, v204
	ds_bpermute_b32 v207, v229, v205
	ds_bpermute_b32 v208, v229, v154
	ds_bpermute_b32 v209, v229, v155
	ds_bpermute_b32 v146, v229, v144
	ds_bpermute_b32 v147, v229, v145
	s_waitcnt lgkmcnt(6)
	v_pk_add_f32 v[150:151], v[150:151], v[152:153]
	s_waitcnt lgkmcnt(4)
	v_pk_add_f32 v[204:205], v[204:205], v[206:207]
	s_waitcnt lgkmcnt(2)
	v_pk_add_f32 v[154:155], v[154:155], v[208:209]
	ds_bpermute_b32 v152, v230, v150
	s_waitcnt lgkmcnt(1)
	v_pk_add_f32 v[144:145], v[144:145], v[146:147]
	ds_bpermute_b32 v153, v230, v151
	ds_bpermute_b32 v206, v230, v204
	ds_bpermute_b32 v207, v230, v205
	ds_bpermute_b32 v208, v230, v154
	ds_bpermute_b32 v209, v230, v155
	ds_bpermute_b32 v146, v230, v144
	ds_bpermute_b32 v147, v230, v145
	s_and_saveexec_b64 s[0:1], vcc
	s_cbranch_execz .LBB0_296
	s_add_u32 s12, s28, s6
	s_waitcnt lgkmcnt(4)
	v_pk_add_f32 v[204:205], v[204:205], v[206:207]
	v_pk_add_f32 v[202:203], v[150:151], v[152:153]
	s_addc_u32 s13, s29, s7
	s_waitcnt lgkmcnt(0)
	v_pk_add_f32 v[146:147], v[144:145], v[146:147]
	v_pk_add_f32 v[144:145], v[154:155], v[208:209]
	global_store_dwordx4 v214, v[202:205], s[12:13]
	global_store_dwordx4 v214, v[144:147], s[12:13] offset:16
	s_branch .LBB0_296
